# grid seams: non-leader workgroups invalidate caches on arrival (before polling the release) instead of after release, so the XCD L2 is invalidated once per seam
# speedup vs baseline: 1.0133x; 1.0042x over previous
; __device__ __forceinline__ unsigned xb_ld(unsigned* p)              { return __hip_atomic_load(p, __ATOMIC_RELAXED, __HIP_MEMORY_SCOPE_AGENT); }
; __device__ __forceinline__ unsigned xb_add(unsigned* p, unsigned v) { return __hip_atomic_fetch_add(p, v, __ATOMIC_RELAXED, __HIP_MEMORY_SCOPE_AGENT); }
; #define XB_SPIN(cond, bar) do { unsigned _sp = 0; while (cond) { __builtin_amdgcn_s_sleep(1); \
;     if ((++_sp & 255u) == 0u) { if (xb_ld(&(bar)[XB_TMO])) break; if (_sp > XB_SPIN_CAP) { atomicAdd(&(bar)[XB_TMO], 1u); break; } } } } while (0)
; __device__ __forceinline__ void xcd_barrier(const XcdBarrier& b) {
;     ...
;         const unsigned old = xb_add(&bar[XB_XSUB(b.x)], 1u);
;         const unsigned gen = old / nloc;
;         if (old + 1u == (gen + 1u) * nloc) {
;             __builtin_amdgcn_fence(__ATOMIC_RELEASE, "agent");
;             asm volatile("s_waitcnt vmcnt(0)" ::: "memory");
;             const unsigned og = xb_add(&bar[XB_TOP], 1u);
;             const unsigned tg = og / nx;
;             if (og + 1u == (tg + 1u) * nx) xb_add(&bar[XB_TOPGEN], 1u);
;             else XB_SPIN(xb_ld(&bar[XB_TOPGEN]) == tg, bar);
;             __builtin_amdgcn_fence(__ATOMIC_ACQUIRE, "agent");
;             xb_add(&bar[XB_XGEN(b.x)], 1u);
;             asm volatile("s_waitcnt vmcnt(0)" ::: "memory");
;         } else {
;             XB_SPIN(xb_ld(&bar[XB_XGEN(b.x)]) == gen, bar);
;             __builtin_amdgcn_fence(__ATOMIC_ACQUIRE, "agent");
;             asm volatile("s_waitcnt vmcnt(0)" ::: "memory");
;         }
.LBB0_258:
	s_or_b64 exec, exec, s[6:7]
	v_cvt_f32_u32_e32 v4, v2
	s_waitcnt vmcnt(0)
	v_readfirstlane_b32 s6, v3
	v_sub_u32_e32 v3, 0, v2
	v_rcp_iflag_f32_e32 v4, v4
	v_add_u32_e32 v5, s6, v1
	v_mul_f32_e32 v4, 0x4f7ffffe, v4
	v_cvt_u32_f32_e32 v4, v4
	v_mul_lo_u32 v1, v3, v4
	v_mul_hi_u32 v1, v4, v1
	v_add_u32_e32 v1, v4, v1
	v_mul_hi_u32 v1, v5, v1
	v_mul_lo_u32 v3, v1, v2
	v_sub_u32_e32 v3, v5, v3
	v_add_u32_e32 v4, 1, v1
	v_cmp_ge_u32_e32 vcc, v3, v2
	s_nop 1
	v_cndmask_b32_e32 v1, v1, v4, vcc
	v_sub_u32_e32 v4, v3, v2
	v_cndmask_b32_e32 v3, v3, v4, vcc
	v_add_u32_e32 v4, 1, v1
	v_cmp_ge_u32_e32 vcc, v3, v2
	v_add_u32_e32 v3, 1, v5
	s_nop 0
	v_cndmask_b32_e32 v1, v1, v4, vcc
	v_mul_lo_u32 v4, v2, v1
	v_add_u32_e32 v2, v4, v2
	v_cmp_ne_u32_e32 vcc, v3, v2
	s_and_saveexec_b64 s[6:7], vcc
	s_xor_b64 s[6:7], exec, s[6:7]
	s_cbranch_execz .LBB0_272
	buffer_inv sc1
	s_waitcnt vmcnt(0)
	v_readlane_b32 s8, v254, 55
	v_readlane_b32 s9, v254, 56
	s_waitcnt lgkmcnt(0)
	s_nop 3
	global_load_dword v0, v145, s[8:9] sc1
	s_waitcnt vmcnt(0)
	v_cmp_eq_u32_e32 vcc, v0, v1
	s_and_saveexec_b64 s[8:9], vcc
	s_cbranch_execz .LBB0_271
	s_mov_b32 s14, 1
	s_mov_b64 s[16:17], 0
	s_branch .LBB0_262

; __device__ __forceinline__ unsigned xb_ld(unsigned* p)              { return __hip_atomic_load(p, __ATOMIC_RELAXED, __HIP_MEMORY_SCOPE_AGENT); }
; #define XB_SPIN(cond, bar) do { unsigned _sp = 0; while (cond) { __builtin_amdgcn_s_sleep(1); \
;     if ((++_sp & 255u) == 0u) { if (xb_ld(&(bar)[XB_TMO])) break; if (_sp > XB_SPIN_CAP) { atomicAdd(&(bar)[XB_TMO], 1u); break; } } } } while (0)
; __device__ __forceinline__ void xcd_barrier(const XcdBarrier& b) {
;     ...
;             XB_SPIN(xb_ld(&bar[XB_XGEN(b.x)]) == gen, bar);
;             __builtin_amdgcn_fence(__ATOMIC_ACQUIRE, "agent");
;             asm volatile("s_waitcnt vmcnt(0)" ::: "memory");
.LBB0_271:
	s_or_b64 exec, exec, s[8:9]
	s_waitcnt vmcnt(0)
	s_waitcnt vmcnt(0)

; __device__ __forceinline__ unsigned xb_ld(unsigned* p)              { return __hip_atomic_load(p, __ATOMIC_RELAXED, __HIP_MEMORY_SCOPE_AGENT); }
; __device__ __forceinline__ unsigned xb_add(unsigned* p, unsigned v) { return __hip_atomic_fetch_add(p, v, __ATOMIC_RELAXED, __HIP_MEMORY_SCOPE_AGENT); }
; #define XB_SPIN(cond, bar) do { unsigned _sp = 0; while (cond) { __builtin_amdgcn_s_sleep(1); \
;     if ((++_sp & 255u) == 0u) { if (xb_ld(&(bar)[XB_TMO])) break; if (_sp > XB_SPIN_CAP) { atomicAdd(&(bar)[XB_TMO], 1u); break; } } } } while (0)
; __device__ __forceinline__ void xcd_barrier(const XcdBarrier& b) {
;     ...
;         const unsigned old = xb_add(&bar[XB_XSUB(b.x)], 1u);
;         const unsigned gen = old / nloc;
;         if (old + 1u == (gen + 1u) * nloc) {
;             __builtin_amdgcn_fence(__ATOMIC_RELEASE, "agent");
;             asm volatile("s_waitcnt vmcnt(0)" ::: "memory");
;             const unsigned og = xb_add(&bar[XB_TOP], 1u);
;             const unsigned tg = og / nx;
;             if (og + 1u == (tg + 1u) * nx) xb_add(&bar[XB_TOPGEN], 1u);
;             else XB_SPIN(xb_ld(&bar[XB_TOPGEN]) == tg, bar);
;             __builtin_amdgcn_fence(__ATOMIC_ACQUIRE, "agent");
;             xb_add(&bar[XB_XGEN(b.x)], 1u);
;             asm volatile("s_waitcnt vmcnt(0)" ::: "memory");
;         } else {
;             XB_SPIN(xb_ld(&bar[XB_XGEN(b.x)]) == gen, bar);
;             __builtin_amdgcn_fence(__ATOMIC_ACQUIRE, "agent");
;             asm volatile("s_waitcnt vmcnt(0)" ::: "memory");
;         }
.LBB0_401:
	s_or_b64 exec, exec, s[6:7]
	v_cvt_f32_u32_e32 v4, v2
	s_waitcnt vmcnt(0)
	v_readfirstlane_b32 s3, v3
	v_sub_u32_e32 v3, 0, v2
	v_rcp_iflag_f32_e32 v4, v4
	v_add_u32_e32 v5, s3, v1
	v_mul_f32_e32 v4, 0x4f7ffffe, v4
	v_cvt_u32_f32_e32 v4, v4
	v_mul_lo_u32 v1, v3, v4
	v_mul_hi_u32 v1, v4, v1
	v_add_u32_e32 v1, v4, v1
	v_mul_hi_u32 v1, v5, v1
	v_mul_lo_u32 v3, v1, v2
	v_sub_u32_e32 v3, v5, v3
	v_add_u32_e32 v4, 1, v1
	v_cmp_ge_u32_e32 vcc, v3, v2
	s_nop 1
	v_cndmask_b32_e32 v1, v1, v4, vcc
	v_sub_u32_e32 v4, v3, v2
	v_cndmask_b32_e32 v3, v3, v4, vcc
	v_add_u32_e32 v4, 1, v1
	v_cmp_ge_u32_e32 vcc, v3, v2
	v_add_u32_e32 v3, 1, v5
	s_nop 0
	v_cndmask_b32_e32 v1, v1, v4, vcc
	v_mul_lo_u32 v4, v2, v1
	v_add_u32_e32 v2, v4, v2
	v_cmp_ne_u32_e32 vcc, v3, v2
	s_and_saveexec_b64 s[6:7], vcc
	s_xor_b64 s[6:7], exec, s[6:7]
	s_cbranch_execz .LBB0_415
	buffer_inv sc1
	s_waitcnt vmcnt(0)
	v_readlane_b32 s8, v254, 55
	v_readlane_b32 s9, v254, 56
	s_waitcnt lgkmcnt(0)
	s_nop 3
	global_load_dword v0, v145, s[8:9] sc1
	s_waitcnt vmcnt(0)
	v_cmp_eq_u32_e32 vcc, v0, v1
	s_and_saveexec_b64 s[8:9], vcc
	s_cbranch_execz .LBB0_414
	s_mov_b32 s3, 1
	s_mov_b64 s[10:11], 0
	s_branch .LBB0_405

; __device__ __forceinline__ unsigned xb_ld(unsigned* p)              { return __hip_atomic_load(p, __ATOMIC_RELAXED, __HIP_MEMORY_SCOPE_AGENT); }
; __device__ __forceinline__ unsigned xb_add(unsigned* p, unsigned v) { return __hip_atomic_fetch_add(p, v, __ATOMIC_RELAXED, __HIP_MEMORY_SCOPE_AGENT); }
; #define XB_SPIN(cond, bar) do { unsigned _sp = 0; while (cond) { __builtin_amdgcn_s_sleep(1); \
;     if ((++_sp & 255u) == 0u) { if (xb_ld(&(bar)[XB_TMO])) break; if (_sp > XB_SPIN_CAP) { atomicAdd(&(bar)[XB_TMO], 1u); break; } } } } while (0)
; __device__ __forceinline__ void xcd_barrier(const XcdBarrier& b) {
;     ...
;         const unsigned old = xb_add(&bar[XB_XSUB(b.x)], 1u);
;         const unsigned gen = old / nloc;
;         if (old + 1u == (gen + 1u) * nloc) {
;             __builtin_amdgcn_fence(__ATOMIC_RELEASE, "agent");
;             asm volatile("s_waitcnt vmcnt(0)" ::: "memory");
;             const unsigned og = xb_add(&bar[XB_TOP], 1u);
;             const unsigned tg = og / nx;
;             if (og + 1u == (tg + 1u) * nx) xb_add(&bar[XB_TOPGEN], 1u);
;             else XB_SPIN(xb_ld(&bar[XB_TOPGEN]) == tg, bar);
;             __builtin_amdgcn_fence(__ATOMIC_ACQUIRE, "agent");
;             xb_add(&bar[XB_XGEN(b.x)], 1u);
;             asm volatile("s_waitcnt vmcnt(0)" ::: "memory");
;         } else {
;             XB_SPIN(xb_ld(&bar[XB_XGEN(b.x)]) == gen, bar);
;             __builtin_amdgcn_fence(__ATOMIC_ACQUIRE, "agent");
;             asm volatile("s_waitcnt vmcnt(0)" ::: "memory");
;         }
.LBB0_502:
	s_or_b64 exec, exec, s[6:7]
	v_cvt_f32_u32_e32 v4, v2
	s_waitcnt vmcnt(0)
	v_readfirstlane_b32 s6, v3
	v_sub_u32_e32 v3, 0, v2
	v_rcp_iflag_f32_e32 v4, v4
	v_add_u32_e32 v5, s6, v1
	v_mul_f32_e32 v4, 0x4f7ffffe, v4
	v_cvt_u32_f32_e32 v4, v4
	v_mul_lo_u32 v1, v3, v4
	v_mul_hi_u32 v1, v4, v1
	v_add_u32_e32 v1, v4, v1
	v_mul_hi_u32 v1, v5, v1
	v_mul_lo_u32 v3, v1, v2
	v_sub_u32_e32 v3, v5, v3
	v_add_u32_e32 v4, 1, v1
	v_cmp_ge_u32_e32 vcc, v3, v2
	s_nop 1
	v_cndmask_b32_e32 v1, v1, v4, vcc
	v_sub_u32_e32 v4, v3, v2
	v_cndmask_b32_e32 v3, v3, v4, vcc
	v_add_u32_e32 v4, 1, v1
	v_cmp_ge_u32_e32 vcc, v3, v2
	v_add_u32_e32 v3, 1, v5
	s_nop 0
	v_cndmask_b32_e32 v1, v1, v4, vcc
	v_mul_lo_u32 v4, v2, v1
	v_add_u32_e32 v2, v4, v2
	v_cmp_ne_u32_e32 vcc, v3, v2
	s_and_saveexec_b64 s[6:7], vcc
	s_xor_b64 s[6:7], exec, s[6:7]
	s_cbranch_execz .LBB0_516
	buffer_inv sc1
	s_waitcnt vmcnt(0)
	v_readlane_b32 s8, v254, 55
	v_readlane_b32 s9, v254, 56
	s_waitcnt lgkmcnt(0)
	s_nop 3
	global_load_dword v0, v145, s[8:9] sc1
	s_waitcnt vmcnt(0)
	v_cmp_eq_u32_e32 vcc, v0, v1
	s_and_saveexec_b64 s[8:9], vcc
	s_cbranch_execz .LBB0_515
	s_mov_b32 s14, 1
	s_mov_b64 s[10:11], 0
	s_branch .LBB0_506
